# P3 QR rope tiles: second-step rope-table loads of each row group hoisted next to the first step's loads (16 exposed load-wait round trips per tile -> 8); on top of p1pk + p8pk + czero
# baseline (speedup 1.0000x reference)
; __device__ __forceinline__ unsigned cvt_pk_bf16(float lo, float hi) { const cvt_f32x2 v = {lo, hi}; const cvt_bf16x2 b = __builtin_convertvector(v, cvt_bf16x2); return __builtin_bit_cast(unsigned, b); }
; #define EPI_ROWLOOP _Pragma("unroll") for (int ai = 0; ai < 2; ++ai) _Pragma("unroll") for (int m = 0; m < 4; ++m)
;     __device__ __forceinline__ void operator()(const f32x4 (&acc)[2][2][4][2], const Unit& u, int wr, int wc, int fr, int fq) const {
;     ...
;             bf16_t* QR = (bf16_t*)(ws + WS_R2); const float* ropecs = (const float*)(ws + WS_ROPE);
;             EPI_ROWLOOP { const int r = row0 + ai * HALF + m * 16; const f32x4 pq = part[r]; const float rs = __builtin_amdgcn_rsqf(((pq[0] + pq[1]) + (pq[2] + pq[3])) * (1.0f / 256.0f) + EP_EPS) * qscale;
;                 const float* t = ropecs + ((size_t)pos_of_row(r) * 32 + 8 * fq) * 2;
;                 bf16_t* rowp = QR + (size_t)r * 512 + (4 * (pn - 4) + wc) * 64 + 8 * fq;
; #pragma unroll
;                 for (int n = 0; n < 2; ++n) { f32x4 a = acc[ai][0][m][n], b = acc[ai][1][m][n]; rope4(a, b, t + 8 * n); a = a * rs; b = b * rs;
;                     *(u32x2*)(rowp + 4 * n) = (u32x2){cvt_pk_bf16(a[0], a[1]), cvt_pk_bf16(a[2], a[3])}; *(u32x2*)(rowp + 32 + 4 * n) = (u32x2){cvt_pk_bf16(b[0], b[1]), cvt_pk_bf16(b[2], b[3])};
;                     asm volatile("" ::: "memory"); } }
.LBB0_541:
	v_lshl_add_u64 v[158:159], v[156:157], 4, s[50:51]
	global_load_dwordx4 v[128:131], v[158:159], off
	v_cmp_lt_i32_e32 vcc, s81, v156
	s_and_saveexec_b64 s[60:61], vcc
	s_xor_b64 s[60:61], exec, s[60:61]
	s_cmp_lt_u32 s59, 0x10010
	v_add_u32_e32 v140, 0xffff0000, v156
	s_cselect_b64 vcc, -1, 0
	v_cndmask_b32_e32 v140, 0, v140, vcc
	s_andn2_saveexec_b64 s[60:61], s[60:61]
	v_and_or_b32 v140, v156, s83, 16
	s_or_b64 exec, exec, s[60:61]
	v_lshlrev_b64 v[160:161], 8, v[140:141]
	v_lshl_add_u64 v[162:163], v[142:143], 0, v[160:161]
	global_load_dwordx4 v[170:173], v[162:163], off offset:16
	global_load_dwordx4 v[174:177], v[162:163], off
	global_load_dwordx4 v[202:205], v[162:163], off offset:48
	global_load_dwordx4 v[206:209], v[162:163], off offset:32
	s_waitcnt vmcnt(0)
	v_add_f32_e32 v128, v128, v129
	v_add_f32_e32 v129, v130, v131
	v_add_f32_e32 v128, v128, v129
	v_fmamk_f32 v128, v128, 0x3b800000, v169
	v_rsq_f32_e32 v130, v128
	s_add_i32 s12, s68, s58
	v_lshlrev_b64 v[128:129], 10, v[156:157]
	v_lshl_add_u64 v[160:161], s[12:13], 1, v[144:145]
	v_lshl_add_u64 v[178:179], v[160:161], 0, v[128:129]
	v_mul_f32_e32 v140, 0x3dd53b94, v130
	v_mov_b32_e32 v128, v171
	v_mov_b32_e32 v129, v173
	v_mov_b32_e32 v130, v175
	v_mov_b32_e32 v131, v177
	v_mov_b32_e32 v175, v176
	v_mov_b32_e32 v171, v172
	v_pk_mul_f32 v[172:173], v[118:119], v[128:129]
	v_pk_mul_f32 v[176:177], v[116:117], v[130:131]
	v_pk_mul_f32 v[180:181], v[118:119], v[170:171]
	v_pk_mul_f32 v[182:183], v[116:117], v[174:175]
	v_pk_fma_f32 v[174:175], v[120:121], v[174:175], v[176:177] neg_lo:[0,0,1] neg_hi:[0,0,1]
	v_pk_fma_f32 v[170:171], v[122:123], v[170:171], v[172:173] neg_lo:[0,0,1] neg_hi:[0,0,1]
	v_pk_fma_f32 v[130:131], v[120:121], v[130:131], v[182:183]
	v_pk_fma_f32 v[128:129], v[122:123], v[128:129], v[180:181]
	v_pk_mul_f32 v[170:171], v[140:141], v[170:171] op_sel_hi:[0,1]
	v_pk_mul_f32 v[172:173], v[140:141], v[174:175] op_sel_hi:[0,1]
	v_pk_mul_f32 v[128:129], v[140:141], v[128:129] op_sel_hi:[0,1]
	v_pk_mul_f32 v[130:131], v[140:141], v[130:131] op_sel_hi:[0,1]
	v_cvt_pk_bf16_f32 v172, v172, v173
	v_cvt_pk_bf16_f32 v173, v170, v171
	v_cvt_pk_bf16_f32 v130, v130, v131
	v_cvt_pk_bf16_f32 v131, v128, v129
	global_store_dwordx2 v[178:179], v[172:173], off
	global_store_dwordx2 v[178:179], v[130:131], off offset:64
	v_or_b32_e32 v162, 16, v156
	v_ashrrev_i32_e32 v163, 31, v162
	v_cmp_lt_i32_e32 vcc, s81, v162
	v_mov_b64_e32 v[128:129], v[202:203]
	v_mov_b64_e32 v[170:171], v[206:207]
	v_mov_b64_e32 v[172:173], v[208:209]
	v_mov_b64_e32 v[130:131], v[204:205]
	v_mov_b32_e32 v174, v129
	v_mov_b32_e32 v175, v131
	v_mov_b32_e32 v176, v171
	v_mov_b32_e32 v177, v173
	v_mov_b32_e32 v171, v172
	v_mov_b32_e32 v129, v130
	v_pk_mul_f32 v[130:131], v[114:115], v[174:175]
	v_pk_mul_f32 v[172:173], v[112:113], v[176:177]
	v_pk_mul_f32 v[180:181], v[114:115], v[128:129]
	v_pk_mul_f32 v[182:183], v[112:113], v[170:171]
	v_pk_fma_f32 v[170:171], v[124:125], v[170:171], v[172:173] neg_lo:[0,0,1] neg_hi:[0,0,1]
	v_pk_fma_f32 v[128:129], v[126:127], v[128:129], v[130:131] neg_lo:[0,0,1] neg_hi:[0,0,1]
	v_pk_fma_f32 v[130:131], v[124:125], v[176:177], v[182:183]
	v_pk_fma_f32 v[172:173], v[126:127], v[174:175], v[180:181]
	v_pk_mul_f32 v[128:129], v[140:141], v[128:129] op_sel_hi:[0,1]
	v_pk_mul_f32 v[170:171], v[140:141], v[170:171] op_sel_hi:[0,1]
	v_pk_mul_f32 v[172:173], v[140:141], v[172:173] op_sel_hi:[0,1]
	v_pk_mul_f32 v[130:131], v[140:141], v[130:131] op_sel_hi:[0,1]
	v_cvt_pk_bf16_f32 v170, v170, v171
	v_cvt_pk_bf16_f32 v171, v128, v129
	v_cvt_pk_bf16_f32 v128, v130, v131
	v_cvt_pk_bf16_f32 v129, v172, v173
	global_store_dwordx2 v[178:179], v[170:171], off offset:8
	global_store_dwordx2 v[178:179], v[128:129], off offset:72
	v_lshl_add_u64 v[128:129], v[162:163], 4, s[50:51]
	global_load_dwordx4 v[128:131], v[128:129], off
	s_and_saveexec_b64 s[60:61], vcc
	s_xor_b64 s[60:61], exec, s[60:61]
	v_add_u32_e32 v140, 0xffff0010, v156
	v_cmp_gt_u32_e32 vcc, s82, v162
	s_nop 1
	v_cndmask_b32_e32 v140, 0, v140, vcc
	s_andn2_saveexec_b64 s[60:61], s[60:61]
	v_and_b32_e32 v140, 0x7df, v162
	v_add_u32_e32 v140, 16, v140
	s_or_b64 exec, exec, s[60:61]
	v_lshlrev_b64 v[170:171], 8, v[140:141]
	v_lshl_add_u64 v[178:179], v[142:143], 0, v[170:171]
	global_load_dwordx4 v[170:173], v[178:179], off offset:16
	global_load_dwordx4 v[174:177], v[178:179], off
	global_load_dwordx4 v[202:205], v[178:179], off offset:48
	global_load_dwordx4 v[206:209], v[178:179], off offset:32
	s_waitcnt vmcnt(0)
; __device__ __forceinline__ unsigned cvt_pk_bf16(float lo, float hi) { const cvt_f32x2 v = {lo, hi}; const cvt_bf16x2 b = __builtin_convertvector(v, cvt_bf16x2); return __builtin_bit_cast(unsigned, b); }
; #define EPI_ROWLOOP _Pragma("unroll") for (int ai = 0; ai < 2; ++ai) _Pragma("unroll") for (int m = 0; m < 4; ++m)
;     __device__ __forceinline__ void operator()(const f32x4 (&acc)[2][2][4][2], const Unit& u, int wr, int wc, int fr, int fq) const {
;     ...
;             bf16_t* QR = (bf16_t*)(ws + WS_R2); const float* ropecs = (const float*)(ws + WS_ROPE);
;             EPI_ROWLOOP { const int r = row0 + ai * HALF + m * 16; const f32x4 pq = part[r]; const float rs = __builtin_amdgcn_rsqf(((pq[0] + pq[1]) + (pq[2] + pq[3])) * (1.0f / 256.0f) + EP_EPS) * qscale;
;                 const float* t = ropecs + ((size_t)pos_of_row(r) * 32 + 8 * fq) * 2;
;                 bf16_t* rowp = QR + (size_t)r * 512 + (4 * (pn - 4) + wc) * 64 + 8 * fq;
; #pragma unroll
;                 for (int n = 0; n < 2; ++n) { f32x4 a = acc[ai][0][m][n], b = acc[ai][1][m][n]; rope4(a, b, t + 8 * n); a = a * rs; b = b * rs;
;                     *(u32x2*)(rowp + 4 * n) = (u32x2){cvt_pk_bf16(a[0], a[1]), cvt_pk_bf16(a[2], a[3])}; *(u32x2*)(rowp + 32 + 4 * n) = (u32x2){cvt_pk_bf16(b[0], b[1]), cvt_pk_bf16(b[2], b[3])};
;                     asm volatile("" ::: "memory"); } }
	v_add_f32_e32 v128, v128, v129
	v_add_f32_e32 v129, v130, v131
	v_add_f32_e32 v128, v128, v129
	v_fmamk_f32 v128, v128, 0x3b800000, v169
	v_rsq_f32_e32 v130, v128
	v_lshlrev_b64 v[128:129], 10, v[162:163]
	v_lshl_add_u64 v[180:181], v[160:161], 0, v[128:129]
	v_mul_f32_e32 v140, 0x3dd53b94, v130
	v_mov_b32_e32 v128, v171
	v_mov_b32_e32 v129, v173
	v_mov_b32_e32 v130, v175
	v_mov_b32_e32 v131, v177
	v_mov_b32_e32 v175, v176
	v_mov_b32_e32 v171, v172
	v_pk_mul_f32 v[162:163], v[102:103], v[128:129]
	v_pk_mul_f32 v[172:173], v[100:101], v[130:131]
	v_pk_mul_f32 v[176:177], v[102:103], v[170:171]
	v_pk_mul_f32 v[182:183], v[100:101], v[174:175]
	v_pk_fma_f32 v[172:173], v[108:109], v[174:175], v[172:173] neg_lo:[0,0,1] neg_hi:[0,0,1]
	v_pk_fma_f32 v[162:163], v[110:111], v[170:171], v[162:163] neg_lo:[0,0,1] neg_hi:[0,0,1]
	v_pk_fma_f32 v[130:131], v[108:109], v[130:131], v[182:183]
	v_pk_fma_f32 v[128:129], v[110:111], v[128:129], v[176:177]
	v_pk_mul_f32 v[162:163], v[140:141], v[162:163] op_sel_hi:[0,1]
	v_pk_mul_f32 v[170:171], v[140:141], v[172:173] op_sel_hi:[0,1]
	v_pk_mul_f32 v[128:129], v[140:141], v[128:129] op_sel_hi:[0,1]
	v_pk_mul_f32 v[130:131], v[140:141], v[130:131] op_sel_hi:[0,1]
	v_cvt_pk_bf16_f32 v170, v170, v171
	v_cvt_pk_bf16_f32 v171, v162, v163
	v_cvt_pk_bf16_f32 v130, v130, v131
	v_cvt_pk_bf16_f32 v131, v128, v129
	global_store_dwordx2 v[180:181], v[170:171], off
	global_store_dwordx2 v[180:181], v[130:131], off offset:64
	v_or_b32_e32 v162, 32, v156
	v_ashrrev_i32_e32 v163, 31, v162
	v_cmp_lt_i32_e32 vcc, s81, v162
	v_mov_b64_e32 v[128:129], v[202:203]
	v_mov_b64_e32 v[170:171], v[206:207]
	v_mov_b64_e32 v[172:173], v[208:209]
	v_mov_b64_e32 v[130:131], v[204:205]
	v_mov_b32_e32 v174, v129
	v_mov_b32_e32 v175, v131
	v_mov_b32_e32 v176, v171
	v_mov_b32_e32 v177, v173
	v_mov_b32_e32 v171, v172
	v_mov_b32_e32 v129, v130
	v_pk_mul_f32 v[130:131], v[98:99], v[174:175]
	v_pk_mul_f32 v[172:173], v[96:97], v[176:177]
	v_pk_mul_f32 v[178:179], v[98:99], v[128:129]
	v_pk_mul_f32 v[182:183], v[96:97], v[170:171]
	v_pk_fma_f32 v[170:171], v[104:105], v[170:171], v[172:173] neg_lo:[0,0,1] neg_hi:[0,0,1]
	v_pk_fma_f32 v[128:129], v[106:107], v[128:129], v[130:131] neg_lo:[0,0,1] neg_hi:[0,0,1]
	v_pk_fma_f32 v[130:131], v[104:105], v[176:177], v[182:183]
	v_pk_fma_f32 v[172:173], v[106:107], v[174:175], v[178:179]
	v_pk_mul_f32 v[128:129], v[140:141], v[128:129] op_sel_hi:[0,1]
	v_pk_mul_f32 v[170:171], v[140:141], v[170:171] op_sel_hi:[0,1]
	v_pk_mul_f32 v[172:173], v[140:141], v[172:173] op_sel_hi:[0,1]
	v_pk_mul_f32 v[130:131], v[140:141], v[130:131] op_sel_hi:[0,1]
	v_cvt_pk_bf16_f32 v170, v170, v171
	v_cvt_pk_bf16_f32 v171, v128, v129
	v_cvt_pk_bf16_f32 v128, v130, v131
	v_cvt_pk_bf16_f32 v129, v172, v173
	global_store_dwordx2 v[180:181], v[170:171], off offset:8
	global_store_dwordx2 v[180:181], v[128:129], off offset:72
	v_lshl_add_u64 v[128:129], v[162:163], 4, s[50:51]
	global_load_dwordx4 v[128:131], v[128:129], off
	s_and_saveexec_b64 s[60:61], vcc
	s_xor_b64 s[60:61], exec, s[60:61]
	v_add_u32_e32 v140, 0xffff0020, v156
	v_cmp_gt_u32_e32 vcc, s82, v162
	s_nop 1
	v_cndmask_b32_e32 v140, 0, v140, vcc
	s_andn2_saveexec_b64 s[60:61], s[60:61]
	v_and_or_b32 v140, v162, s84, 16
	s_or_b64 exec, exec, s[60:61]
	v_lshlrev_b64 v[170:171], 8, v[140:141]
	v_lshl_add_u64 v[178:179], v[142:143], 0, v[170:171]
	global_load_dwordx4 v[170:173], v[178:179], off offset:16
	global_load_dwordx4 v[174:177], v[178:179], off
	global_load_dwordx4 v[202:205], v[178:179], off offset:48
	global_load_dwordx4 v[206:209], v[178:179], off offset:32
	s_waitcnt vmcnt(0)
	v_add_f32_e32 v128, v128, v129
	v_add_f32_e32 v129, v130, v131
	v_add_f32_e32 v128, v128, v129
	v_fmamk_f32 v128, v128, 0x3b800000, v169
	v_rsq_f32_e32 v130, v128
	v_lshlrev_b64 v[128:129], 10, v[162:163]
	v_lshl_add_u64 v[180:181], v[160:161], 0, v[128:129]
	v_mul_f32_e32 v140, 0x3dd53b94, v130
	v_mov_b32_e32 v128, v171
	v_mov_b32_e32 v129, v173
	v_mov_b32_e32 v130, v175
	v_mov_b32_e32 v131, v177
	v_mov_b32_e32 v175, v176
	v_mov_b32_e32 v171, v172
	v_pk_mul_f32 v[162:163], v[86:87], v[128:129]
	v_pk_mul_f32 v[172:173], v[84:85], v[130:131]
	v_pk_mul_f32 v[176:177], v[86:87], v[170:171]
	v_pk_mul_f32 v[182:183], v[84:85], v[174:175]
	v_pk_fma_f32 v[172:173], v[92:93], v[174:175], v[172:173] neg_lo:[0,0,1] neg_hi:[0,0,1]
	v_pk_fma_f32 v[162:163], v[94:95], v[170:171], v[162:163] neg_lo:[0,0,1] neg_hi:[0,0,1]
	v_pk_fma_f32 v[130:131], v[92:93], v[130:131], v[182:183]
	v_pk_fma_f32 v[128:129], v[94:95], v[128:129], v[176:177]
	v_pk_mul_f32 v[162:163], v[140:141], v[162:163] op_sel_hi:[0,1]
	v_pk_mul_f32 v[170:171], v[140:141], v[172:173] op_sel_hi:[0,1]
	v_pk_mul_f32 v[128:129], v[140:141], v[128:129] op_sel_hi:[0,1]
	v_pk_mul_f32 v[130:131], v[140:141], v[130:131] op_sel_hi:[0,1]
	v_cvt_pk_bf16_f32 v170, v170, v171
	v_cvt_pk_bf16_f32 v171, v162, v163
	v_cvt_pk_bf16_f32 v130, v130, v131
	v_cvt_pk_bf16_f32 v131, v128, v129
	global_store_dwordx2 v[180:181], v[170:171], off
	global_store_dwordx2 v[180:181], v[130:131], off offset:64
	v_or_b32_e32 v162, 48, v156
	v_ashrrev_i32_e32 v163, 31, v162
	v_cmp_lt_i32_e32 vcc, s81, v162
	v_mov_b64_e32 v[128:129], v[202:203]
	v_mov_b64_e32 v[170:171], v[206:207]
	v_mov_b64_e32 v[172:173], v[208:209]
	v_mov_b64_e32 v[130:131], v[204:205]
	v_mov_b32_e32 v174, v129
	v_mov_b32_e32 v175, v131
	v_mov_b32_e32 v176, v171
	v_mov_b32_e32 v177, v173
	v_mov_b32_e32 v171, v172
	v_mov_b32_e32 v129, v130
	v_pk_mul_f32 v[130:131], v[82:83], v[174:175]
	v_pk_mul_f32 v[172:173], v[80:81], v[176:177]
	v_pk_mul_f32 v[178:179], v[82:83], v[128:129]
; __device__ __forceinline__ unsigned cvt_pk_bf16(float lo, float hi) { const cvt_f32x2 v = {lo, hi}; const cvt_bf16x2 b = __builtin_convertvector(v, cvt_bf16x2); return __builtin_bit_cast(unsigned, b); }
; #define EPI_ROWLOOP _Pragma("unroll") for (int ai = 0; ai < 2; ++ai) _Pragma("unroll") for (int m = 0; m < 4; ++m)
;     __device__ __forceinline__ void operator()(const f32x4 (&acc)[2][2][4][2], const Unit& u, int wr, int wc, int fr, int fq) const {
;     ...
;             bf16_t* QR = (bf16_t*)(ws + WS_R2); const float* ropecs = (const float*)(ws + WS_ROPE);
;             EPI_ROWLOOP { const int r = row0 + ai * HALF + m * 16; const f32x4 pq = part[r]; const float rs = __builtin_amdgcn_rsqf(((pq[0] + pq[1]) + (pq[2] + pq[3])) * (1.0f / 256.0f) + EP_EPS) * qscale;
;                 const float* t = ropecs + ((size_t)pos_of_row(r) * 32 + 8 * fq) * 2;
;                 bf16_t* rowp = QR + (size_t)r * 512 + (4 * (pn - 4) + wc) * 64 + 8 * fq;
; #pragma unroll
;                 for (int n = 0; n < 2; ++n) { f32x4 a = acc[ai][0][m][n], b = acc[ai][1][m][n]; rope4(a, b, t + 8 * n); a = a * rs; b = b * rs;
;                     *(u32x2*)(rowp + 4 * n) = (u32x2){cvt_pk_bf16(a[0], a[1]), cvt_pk_bf16(a[2], a[3])}; *(u32x2*)(rowp + 32 + 4 * n) = (u32x2){cvt_pk_bf16(b[0], b[1]), cvt_pk_bf16(b[2], b[3])};
;                     asm volatile("" ::: "memory"); } }
	v_pk_mul_f32 v[182:183], v[80:81], v[170:171]
	v_pk_fma_f32 v[170:171], v[88:89], v[170:171], v[172:173] neg_lo:[0,0,1] neg_hi:[0,0,1]
	v_pk_fma_f32 v[128:129], v[90:91], v[128:129], v[130:131] neg_lo:[0,0,1] neg_hi:[0,0,1]
	v_pk_fma_f32 v[130:131], v[88:89], v[176:177], v[182:183]
	v_pk_fma_f32 v[172:173], v[90:91], v[174:175], v[178:179]
	v_pk_mul_f32 v[128:129], v[140:141], v[128:129] op_sel_hi:[0,1]
	v_pk_mul_f32 v[170:171], v[140:141], v[170:171] op_sel_hi:[0,1]
	v_pk_mul_f32 v[172:173], v[140:141], v[172:173] op_sel_hi:[0,1]
	v_pk_mul_f32 v[130:131], v[140:141], v[130:131] op_sel_hi:[0,1]
	v_cvt_pk_bf16_f32 v170, v170, v171
	v_cvt_pk_bf16_f32 v171, v128, v129
	v_cvt_pk_bf16_f32 v128, v130, v131
	v_cvt_pk_bf16_f32 v129, v172, v173
	global_store_dwordx2 v[180:181], v[170:171], off offset:8
	global_store_dwordx2 v[180:181], v[128:129], off offset:72
	v_lshl_add_u64 v[128:129], v[162:163], 4, s[50:51]
	global_load_dwordx4 v[128:131], v[128:129], off
	s_and_saveexec_b64 s[60:61], vcc
	s_xor_b64 s[60:61], exec, s[60:61]
	v_add_u32_e32 v140, 0xffff0030, v156
	v_cmp_gt_u32_e32 vcc, s82, v162
	s_nop 1
	v_cndmask_b32_e32 v140, 0, v140, vcc
	s_andn2_saveexec_b64 s[60:61], s[60:61]
	v_and_b32_e32 v140, 0x7ff, v162
	v_add_u32_e32 v140, 16, v140
	s_or_b64 exec, exec, s[60:61]
	v_lshlrev_b64 v[170:171], 8, v[140:141]
	v_lshl_add_u64 v[178:179], v[142:143], 0, v[170:171]
	global_load_dwordx4 v[170:173], v[178:179], off offset:16
	global_load_dwordx4 v[174:177], v[178:179], off
	global_load_dwordx4 v[202:205], v[178:179], off offset:48
	global_load_dwordx4 v[206:209], v[178:179], off offset:32
	s_waitcnt vmcnt(0)
	v_add_f32_e32 v128, v128, v129
	v_add_f32_e32 v129, v130, v131
	v_add_f32_e32 v128, v128, v129
	v_fmamk_f32 v128, v128, 0x3b800000, v169
	v_rsq_f32_e32 v130, v128
	v_lshlrev_b64 v[128:129], 10, v[162:163]
	v_lshl_add_u64 v[162:163], v[160:161], 0, v[128:129]
	s_mov_b32 s12, 0xff7f
	v_mul_f32_e32 v140, 0x3dd53b94, v130
	v_cmp_lt_i32_e32 vcc, s12, v156
	v_mov_b32_e32 v128, v171
	v_mov_b32_e32 v129, v173
	v_mov_b32_e32 v130, v175
	v_mov_b32_e32 v131, v177
	v_mov_b32_e32 v175, v176
	v_mov_b32_e32 v171, v172
	v_pk_mul_f32 v[172:173], v[70:71], v[128:129]
	v_pk_mul_f32 v[176:177], v[68:69], v[130:131]
	v_pk_mul_f32 v[180:181], v[70:71], v[170:171]
	v_pk_mul_f32 v[182:183], v[68:69], v[174:175]
	v_pk_fma_f32 v[174:175], v[76:77], v[174:175], v[176:177] neg_lo:[0,0,1] neg_hi:[0,0,1]
	v_pk_fma_f32 v[170:171], v[78:79], v[170:171], v[172:173] neg_lo:[0,0,1] neg_hi:[0,0,1]
	v_pk_fma_f32 v[130:131], v[76:77], v[130:131], v[182:183]
	v_pk_fma_f32 v[128:129], v[78:79], v[128:129], v[180:181]
	v_pk_mul_f32 v[170:171], v[140:141], v[170:171] op_sel_hi:[0,1]
	v_pk_mul_f32 v[172:173], v[140:141], v[174:175] op_sel_hi:[0,1]
	v_pk_mul_f32 v[128:129], v[140:141], v[128:129] op_sel_hi:[0,1]
	v_pk_mul_f32 v[130:131], v[140:141], v[130:131] op_sel_hi:[0,1]
	v_cvt_pk_bf16_f32 v172, v172, v173
	v_cvt_pk_bf16_f32 v173, v170, v171
	v_cvt_pk_bf16_f32 v130, v130, v131
	v_cvt_pk_bf16_f32 v131, v128, v129
	global_store_dwordx2 v[162:163], v[172:173], off
	global_store_dwordx2 v[162:163], v[130:131], off offset:64
	v_mov_b64_e32 v[128:129], v[202:203]
	v_mov_b64_e32 v[170:171], v[206:207]
	v_mov_b64_e32 v[130:131], v[204:205]
	v_mov_b64_e32 v[172:173], v[208:209]
	v_mov_b32_e32 v174, v129
	v_mov_b32_e32 v175, v131
	v_mov_b32_e32 v176, v171
	v_mov_b32_e32 v177, v173
	v_mov_b32_e32 v171, v172
	v_mov_b32_e32 v129, v130
	v_pk_mul_f32 v[130:131], v[66:67], v[174:175]
	v_pk_mul_f32 v[172:173], v[64:65], v[176:177]
	v_pk_mul_f32 v[178:179], v[66:67], v[128:129]
	v_pk_mul_f32 v[180:181], v[64:65], v[170:171]
	v_pk_fma_f32 v[170:171], v[72:73], v[170:171], v[172:173] neg_lo:[0,0,1] neg_hi:[0,0,1]
	v_pk_fma_f32 v[128:129], v[74:75], v[128:129], v[130:131] neg_lo:[0,0,1] neg_hi:[0,0,1]
	v_pk_fma_f32 v[130:131], v[72:73], v[176:177], v[180:181]
	v_pk_fma_f32 v[172:173], v[74:75], v[174:175], v[178:179]
	v_pk_mul_f32 v[128:129], v[140:141], v[128:129] op_sel_hi:[0,1]
	v_pk_mul_f32 v[170:171], v[140:141], v[170:171] op_sel_hi:[0,1]
	v_pk_mul_f32 v[172:173], v[140:141], v[172:173] op_sel_hi:[0,1]
	v_pk_mul_f32 v[130:131], v[140:141], v[130:131] op_sel_hi:[0,1]
	v_cvt_pk_bf16_f32 v170, v170, v171
	v_cvt_pk_bf16_f32 v171, v128, v129
	v_cvt_pk_bf16_f32 v128, v130, v131
	v_cvt_pk_bf16_f32 v129, v172, v173
	global_store_dwordx2 v[162:163], v[170:171], off offset:8
	global_store_dwordx2 v[162:163], v[128:129], off offset:72
	global_load_dwordx4 v[128:131], v[158:159], off offset:2048
	v_add_u32_e32 v162, 0x80, v156
	v_ashrrev_i32_e32 v163, 31, v162
	s_and_saveexec_b64 s[60:61], vcc
	s_xor_b64 s[60:61], exec, s[60:61]
	v_add_u32_e32 v140, 0xffff0080, v156
	v_cmp_gt_u32_e32 vcc, s82, v162
	s_nop 1
	v_cndmask_b32_e32 v140, 0, v140, vcc
	s_andn2_saveexec_b64 s[60:61], s[60:61]
	v_and_or_b32 v140, v162, s83, 16
	s_or_b64 exec, exec, s[60:61]
	v_lshlrev_b64 v[170:171], 8, v[140:141]
	v_lshl_add_u64 v[178:179], v[142:143], 0, v[170:171]
	global_load_dwordx4 v[170:173], v[178:179], off offset:16
	global_load_dwordx4 v[174:177], v[178:179], off
	global_load_dwordx4 v[202:205], v[178:179], off offset:48
	global_load_dwordx4 v[206:209], v[178:179], off offset:32
	s_waitcnt vmcnt(0)
; __device__ __forceinline__ unsigned cvt_pk_bf16(float lo, float hi) { const cvt_f32x2 v = {lo, hi}; const cvt_bf16x2 b = __builtin_convertvector(v, cvt_bf16x2); return __builtin_bit_cast(unsigned, b); }
; #define EPI_ROWLOOP _Pragma("unroll") for (int ai = 0; ai < 2; ++ai) _Pragma("unroll") for (int m = 0; m < 4; ++m)
;     __device__ __forceinline__ void operator()(const f32x4 (&acc)[2][2][4][2], const Unit& u, int wr, int wc, int fr, int fq) const {
;     ...
;             bf16_t* QR = (bf16_t*)(ws + WS_R2); const float* ropecs = (const float*)(ws + WS_ROPE);
;             EPI_ROWLOOP { const int r = row0 + ai * HALF + m * 16; const f32x4 pq = part[r]; const float rs = __builtin_amdgcn_rsqf(((pq[0] + pq[1]) + (pq[2] + pq[3])) * (1.0f / 256.0f) + EP_EPS) * qscale;
;                 const float* t = ropecs + ((size_t)pos_of_row(r) * 32 + 8 * fq) * 2;
;                 bf16_t* rowp = QR + (size_t)r * 512 + (4 * (pn - 4) + wc) * 64 + 8 * fq;
; #pragma unroll
;                 for (int n = 0; n < 2; ++n) { f32x4 a = acc[ai][0][m][n], b = acc[ai][1][m][n]; rope4(a, b, t + 8 * n); a = a * rs; b = b * rs;
;                     *(u32x2*)(rowp + 4 * n) = (u32x2){cvt_pk_bf16(a[0], a[1]), cvt_pk_bf16(a[2], a[3])}; *(u32x2*)(rowp + 32 + 4 * n) = (u32x2){cvt_pk_bf16(b[0], b[1]), cvt_pk_bf16(b[2], b[3])};
;                     asm volatile("" ::: "memory"); } }
	v_add_f32_e32 v128, v128, v129
	v_add_f32_e32 v129, v130, v131
	v_add_f32_e32 v128, v128, v129
	v_fmamk_f32 v128, v128, 0x3b800000, v169
	v_rsq_f32_e32 v130, v128
	v_lshlrev_b64 v[128:129], 10, v[162:163]
	v_lshl_add_u64 v[162:163], v[160:161], 0, v[128:129]
	s_mov_b32 s12, 0xff6f
	v_mul_f32_e32 v140, 0x3dd53b94, v130
	v_cmp_lt_i32_e32 vcc, s12, v156
	v_mov_b32_e32 v128, v171
	v_mov_b32_e32 v129, v173
	v_mov_b32_e32 v130, v175
	v_mov_b32_e32 v131, v177
	v_mov_b32_e32 v175, v176
	v_mov_b32_e32 v171, v172
	v_pk_mul_f32 v[172:173], v[54:55], v[128:129]
	v_pk_mul_f32 v[176:177], v[52:53], v[130:131]
	v_pk_mul_f32 v[180:181], v[54:55], v[170:171]
	v_pk_mul_f32 v[182:183], v[52:53], v[174:175]
	v_pk_fma_f32 v[174:175], v[60:61], v[174:175], v[176:177] neg_lo:[0,0,1] neg_hi:[0,0,1]
	v_pk_fma_f32 v[170:171], v[62:63], v[170:171], v[172:173] neg_lo:[0,0,1] neg_hi:[0,0,1]
	v_pk_fma_f32 v[130:131], v[60:61], v[130:131], v[182:183]
	v_pk_fma_f32 v[128:129], v[62:63], v[128:129], v[180:181]
	v_pk_mul_f32 v[170:171], v[140:141], v[170:171] op_sel_hi:[0,1]
	v_pk_mul_f32 v[172:173], v[140:141], v[174:175] op_sel_hi:[0,1]
	v_pk_mul_f32 v[128:129], v[140:141], v[128:129] op_sel_hi:[0,1]
	v_pk_mul_f32 v[130:131], v[140:141], v[130:131] op_sel_hi:[0,1]
	v_cvt_pk_bf16_f32 v172, v172, v173
	v_cvt_pk_bf16_f32 v173, v170, v171
	v_cvt_pk_bf16_f32 v130, v130, v131
	v_cvt_pk_bf16_f32 v131, v128, v129
	global_store_dwordx2 v[162:163], v[172:173], off
	global_store_dwordx2 v[162:163], v[130:131], off offset:64
	v_mov_b64_e32 v[128:129], v[202:203]
	v_mov_b64_e32 v[170:171], v[206:207]
	v_mov_b64_e32 v[130:131], v[204:205]
	v_mov_b64_e32 v[172:173], v[208:209]
	v_mov_b32_e32 v174, v129
	v_mov_b32_e32 v175, v131
	v_mov_b32_e32 v176, v171
	v_mov_b32_e32 v177, v173
	v_mov_b32_e32 v171, v172
	v_mov_b32_e32 v129, v130
	v_pk_mul_f32 v[130:131], v[50:51], v[174:175]
	v_pk_mul_f32 v[172:173], v[48:49], v[176:177]
	v_pk_mul_f32 v[178:179], v[50:51], v[128:129]
	v_pk_mul_f32 v[180:181], v[48:49], v[170:171]
	v_pk_fma_f32 v[170:171], v[56:57], v[170:171], v[172:173] neg_lo:[0,0,1] neg_hi:[0,0,1]
	v_pk_fma_f32 v[128:129], v[58:59], v[128:129], v[130:131] neg_lo:[0,0,1] neg_hi:[0,0,1]
	v_pk_fma_f32 v[130:131], v[56:57], v[176:177], v[180:181]
	v_pk_fma_f32 v[172:173], v[58:59], v[174:175], v[178:179]
	v_pk_mul_f32 v[128:129], v[140:141], v[128:129] op_sel_hi:[0,1]
	v_pk_mul_f32 v[170:171], v[140:141], v[170:171] op_sel_hi:[0,1]
	v_pk_mul_f32 v[172:173], v[140:141], v[172:173] op_sel_hi:[0,1]
	v_pk_mul_f32 v[130:131], v[140:141], v[130:131] op_sel_hi:[0,1]
	v_cvt_pk_bf16_f32 v170, v170, v171
	v_cvt_pk_bf16_f32 v171, v128, v129
	v_cvt_pk_bf16_f32 v128, v130, v131
	v_cvt_pk_bf16_f32 v129, v172, v173
	global_store_dwordx2 v[162:163], v[170:171], off offset:8
	global_store_dwordx2 v[162:163], v[128:129], off offset:72
	global_load_dwordx4 v[128:131], v[158:159], off offset:2304
	v_add_u32_e32 v162, 0x90, v156
	v_ashrrev_i32_e32 v163, 31, v162
	s_and_saveexec_b64 s[60:61], vcc
	s_xor_b64 s[60:61], exec, s[60:61]
	v_add_u32_e32 v140, 0xffff0090, v156
	v_cmp_gt_u32_e32 vcc, s82, v162
	s_nop 1
	v_cndmask_b32_e32 v140, 0, v140, vcc
	s_andn2_saveexec_b64 s[60:61], s[60:61]
	v_and_b32_e32 v140, 0x7df, v162
	v_add_u32_e32 v140, 16, v140
	s_or_b64 exec, exec, s[60:61]
	v_lshlrev_b64 v[170:171], 8, v[140:141]
	v_lshl_add_u64 v[178:179], v[142:143], 0, v[170:171]
	global_load_dwordx4 v[170:173], v[178:179], off offset:16
	global_load_dwordx4 v[174:177], v[178:179], off
	global_load_dwordx4 v[202:205], v[178:179], off offset:48
	global_load_dwordx4 v[206:209], v[178:179], off offset:32
	s_waitcnt vmcnt(0)
	v_add_f32_e32 v128, v128, v129
	v_add_f32_e32 v129, v130, v131
	v_add_f32_e32 v128, v128, v129
	v_fmamk_f32 v128, v128, 0x3b800000, v169
	v_rsq_f32_e32 v130, v128
	v_lshlrev_b64 v[128:129], 10, v[162:163]
	v_lshl_add_u64 v[162:163], v[160:161], 0, v[128:129]
	s_mov_b32 s12, 0xff5f
	v_mul_f32_e32 v140, 0x3dd53b94, v130
	v_cmp_lt_i32_e32 vcc, s12, v156
	v_mov_b32_e32 v128, v171
	v_mov_b32_e32 v129, v173
	v_mov_b32_e32 v130, v175
	v_mov_b32_e32 v131, v177
	v_mov_b32_e32 v175, v176
	v_mov_b32_e32 v171, v172
	v_pk_mul_f32 v[172:173], v[38:39], v[128:129]
	v_pk_mul_f32 v[176:177], v[36:37], v[130:131]
	v_pk_mul_f32 v[180:181], v[38:39], v[170:171]
	v_pk_mul_f32 v[182:183], v[36:37], v[174:175]
	v_pk_fma_f32 v[174:175], v[44:45], v[174:175], v[176:177] neg_lo:[0,0,1] neg_hi:[0,0,1]
	v_pk_fma_f32 v[170:171], v[46:47], v[170:171], v[172:173] neg_lo:[0,0,1] neg_hi:[0,0,1]
	v_pk_fma_f32 v[130:131], v[44:45], v[130:131], v[182:183]
	v_pk_fma_f32 v[128:129], v[46:47], v[128:129], v[180:181]
	v_pk_mul_f32 v[170:171], v[140:141], v[170:171] op_sel_hi:[0,1]
	v_pk_mul_f32 v[172:173], v[140:141], v[174:175] op_sel_hi:[0,1]
	v_pk_mul_f32 v[128:129], v[140:141], v[128:129] op_sel_hi:[0,1]
	v_pk_mul_f32 v[130:131], v[140:141], v[130:131] op_sel_hi:[0,1]
	v_cvt_pk_bf16_f32 v172, v172, v173
	v_cvt_pk_bf16_f32 v173, v170, v171
	v_cvt_pk_bf16_f32 v130, v130, v131
	v_cvt_pk_bf16_f32 v131, v128, v129
	global_store_dwordx2 v[162:163], v[172:173], off
	global_store_dwordx2 v[162:163], v[130:131], off offset:64
	v_mov_b64_e32 v[128:129], v[202:203]
	v_mov_b64_e32 v[170:171], v[206:207]
	v_mov_b64_e32 v[130:131], v[204:205]
	v_mov_b64_e32 v[172:173], v[208:209]
	v_mov_b32_e32 v174, v129
	v_mov_b32_e32 v175, v131
	v_mov_b32_e32 v176, v171
	v_mov_b32_e32 v177, v173
	v_mov_b32_e32 v171, v172
	v_mov_b32_e32 v129, v130
	v_pk_mul_f32 v[130:131], v[34:35], v[174:175]
	v_pk_mul_f32 v[172:173], v[32:33], v[176:177]
	v_pk_mul_f32 v[178:179], v[34:35], v[128:129]
	v_pk_mul_f32 v[180:181], v[32:33], v[170:171]
; __device__ __forceinline__ unsigned cvt_pk_bf16(float lo, float hi) { const cvt_f32x2 v = {lo, hi}; const cvt_bf16x2 b = __builtin_convertvector(v, cvt_bf16x2); return __builtin_bit_cast(unsigned, b); }
; #define EPI_ROWLOOP _Pragma("unroll") for (int ai = 0; ai < 2; ++ai) _Pragma("unroll") for (int m = 0; m < 4; ++m)
;     __device__ __forceinline__ void operator()(const f32x4 (&acc)[2][2][4][2], const Unit& u, int wr, int wc, int fr, int fq) const {
;     ...
;             bf16_t* QR = (bf16_t*)(ws + WS_R2); const float* ropecs = (const float*)(ws + WS_ROPE);
;             EPI_ROWLOOP { const int r = row0 + ai * HALF + m * 16; const f32x4 pq = part[r]; const float rs = __builtin_amdgcn_rsqf(((pq[0] + pq[1]) + (pq[2] + pq[3])) * (1.0f / 256.0f) + EP_EPS) * qscale;
;                 const float* t = ropecs + ((size_t)pos_of_row(r) * 32 + 8 * fq) * 2;
;                 bf16_t* rowp = QR + (size_t)r * 512 + (4 * (pn - 4) + wc) * 64 + 8 * fq;
; #pragma unroll
;                 for (int n = 0; n < 2; ++n) { f32x4 a = acc[ai][0][m][n], b = acc[ai][1][m][n]; rope4(a, b, t + 8 * n); a = a * rs; b = b * rs;
;                     *(u32x2*)(rowp + 4 * n) = (u32x2){cvt_pk_bf16(a[0], a[1]), cvt_pk_bf16(a[2], a[3])}; *(u32x2*)(rowp + 32 + 4 * n) = (u32x2){cvt_pk_bf16(b[0], b[1]), cvt_pk_bf16(b[2], b[3])};
;                     asm volatile("" ::: "memory"); } }
	v_pk_fma_f32 v[170:171], v[40:41], v[170:171], v[172:173] neg_lo:[0,0,1] neg_hi:[0,0,1]
	v_pk_fma_f32 v[128:129], v[42:43], v[128:129], v[130:131] neg_lo:[0,0,1] neg_hi:[0,0,1]
	v_pk_fma_f32 v[130:131], v[40:41], v[176:177], v[180:181]
	v_pk_fma_f32 v[172:173], v[42:43], v[174:175], v[178:179]
	v_pk_mul_f32 v[128:129], v[140:141], v[128:129] op_sel_hi:[0,1]
	v_pk_mul_f32 v[170:171], v[140:141], v[170:171] op_sel_hi:[0,1]
	v_pk_mul_f32 v[172:173], v[140:141], v[172:173] op_sel_hi:[0,1]
	v_pk_mul_f32 v[130:131], v[140:141], v[130:131] op_sel_hi:[0,1]
	v_cvt_pk_bf16_f32 v170, v170, v171
	v_cvt_pk_bf16_f32 v171, v128, v129
	v_cvt_pk_bf16_f32 v128, v130, v131
	v_cvt_pk_bf16_f32 v129, v172, v173
	global_store_dwordx2 v[162:163], v[170:171], off offset:8
	global_store_dwordx2 v[162:163], v[128:129], off offset:72
	global_load_dwordx4 v[128:131], v[158:159], off offset:2560
	v_add_u32_e32 v162, 0xa0, v156
	v_ashrrev_i32_e32 v163, 31, v162
	s_and_saveexec_b64 s[60:61], vcc
	s_xor_b64 s[60:61], exec, s[60:61]
	v_add_u32_e32 v140, 0xffff00a0, v156
	v_cmp_gt_u32_e32 vcc, s82, v162
	s_nop 1
	v_cndmask_b32_e32 v140, 0, v140, vcc
	s_andn2_saveexec_b64 s[60:61], s[60:61]
	v_and_or_b32 v140, v162, s84, 16
	s_or_b64 exec, exec, s[60:61]
	v_lshlrev_b64 v[170:171], 8, v[140:141]
	v_lshl_add_u64 v[178:179], v[142:143], 0, v[170:171]
	global_load_dwordx4 v[170:173], v[178:179], off offset:16
	global_load_dwordx4 v[174:177], v[178:179], off
	global_load_dwordx4 v[202:205], v[178:179], off offset:48
	global_load_dwordx4 v[206:209], v[178:179], off offset:32
	s_waitcnt vmcnt(0)
	v_add_f32_e32 v128, v128, v129
	v_add_f32_e32 v129, v130, v131
	v_add_f32_e32 v128, v128, v129
	v_fmamk_f32 v128, v128, 0x3b800000, v169
	v_rsq_f32_e32 v130, v128
	v_lshlrev_b64 v[128:129], 10, v[162:163]
	v_lshl_add_u64 v[162:163], v[160:161], 0, v[128:129]
	s_mov_b32 s12, 0xff4f
	v_mul_f32_e32 v140, 0x3dd53b94, v130
	v_cmp_lt_i32_e32 vcc, s12, v156
	v_mov_b32_e32 v128, v171
	v_mov_b32_e32 v129, v173
	v_mov_b32_e32 v130, v175
	v_mov_b32_e32 v131, v177
	v_mov_b32_e32 v175, v176
	v_mov_b32_e32 v171, v172
	v_pk_mul_f32 v[172:173], v[22:23], v[128:129]
	v_pk_mul_f32 v[176:177], v[20:21], v[130:131]
	v_pk_mul_f32 v[180:181], v[22:23], v[170:171]
	v_pk_mul_f32 v[182:183], v[20:21], v[174:175]
	v_pk_fma_f32 v[174:175], v[28:29], v[174:175], v[176:177] neg_lo:[0,0,1] neg_hi:[0,0,1]
	v_pk_fma_f32 v[170:171], v[30:31], v[170:171], v[172:173] neg_lo:[0,0,1] neg_hi:[0,0,1]
	v_pk_fma_f32 v[130:131], v[28:29], v[130:131], v[182:183]
	v_pk_fma_f32 v[128:129], v[30:31], v[128:129], v[180:181]
	v_pk_mul_f32 v[170:171], v[140:141], v[170:171] op_sel_hi:[0,1]
	v_pk_mul_f32 v[172:173], v[140:141], v[174:175] op_sel_hi:[0,1]
	v_pk_mul_f32 v[128:129], v[140:141], v[128:129] op_sel_hi:[0,1]
	v_pk_mul_f32 v[130:131], v[140:141], v[130:131] op_sel_hi:[0,1]
	v_cvt_pk_bf16_f32 v172, v172, v173
	v_cvt_pk_bf16_f32 v173, v170, v171
	v_cvt_pk_bf16_f32 v130, v130, v131
	v_cvt_pk_bf16_f32 v131, v128, v129
	global_store_dwordx2 v[162:163], v[172:173], off
	global_store_dwordx2 v[162:163], v[130:131], off offset:64
	v_mov_b64_e32 v[128:129], v[202:203]
	v_mov_b64_e32 v[170:171], v[206:207]
	v_mov_b64_e32 v[130:131], v[204:205]
	v_mov_b64_e32 v[172:173], v[208:209]
	v_mov_b32_e32 v174, v129
	v_mov_b32_e32 v175, v131
	v_mov_b32_e32 v176, v171
	v_mov_b32_e32 v177, v173
	v_mov_b32_e32 v171, v172
	v_mov_b32_e32 v129, v130
	v_pk_mul_f32 v[130:131], v[18:19], v[174:175]
	v_pk_mul_f32 v[172:173], v[16:17], v[176:177]
	v_pk_mul_f32 v[178:179], v[18:19], v[128:129]
	v_pk_mul_f32 v[180:181], v[16:17], v[170:171]
	v_pk_fma_f32 v[170:171], v[24:25], v[170:171], v[172:173] neg_lo:[0,0,1] neg_hi:[0,0,1]
	v_pk_fma_f32 v[128:129], v[26:27], v[128:129], v[130:131] neg_lo:[0,0,1] neg_hi:[0,0,1]
	v_pk_fma_f32 v[130:131], v[24:25], v[176:177], v[180:181]
	v_pk_fma_f32 v[172:173], v[26:27], v[174:175], v[178:179]
	v_pk_mul_f32 v[128:129], v[140:141], v[128:129] op_sel_hi:[0,1]
	v_pk_mul_f32 v[170:171], v[140:141], v[170:171] op_sel_hi:[0,1]
	v_pk_mul_f32 v[172:173], v[140:141], v[172:173] op_sel_hi:[0,1]
	v_pk_mul_f32 v[130:131], v[140:141], v[130:131] op_sel_hi:[0,1]
	v_cvt_pk_bf16_f32 v170, v170, v171
	v_cvt_pk_bf16_f32 v171, v128, v129
	v_cvt_pk_bf16_f32 v128, v130, v131
	v_cvt_pk_bf16_f32 v129, v172, v173
	global_store_dwordx2 v[162:163], v[170:171], off offset:8
	global_store_dwordx2 v[162:163], v[128:129], off offset:72
	global_load_dwordx4 v[128:131], v[158:159], off offset:2816
	v_add_u32_e32 v158, 0xb0, v156
	v_ashrrev_i32_e32 v159, 31, v158
	s_and_saveexec_b64 s[60:61], vcc
	s_xor_b64 s[60:61], exec, s[60:61]
	v_add_u32_e32 v140, 0xffff00b0, v156
	v_cmp_gt_u32_e32 vcc, s82, v158
	s_nop 1
	v_cndmask_b32_e32 v140, 0, v140, vcc
	s_andn2_saveexec_b64 s[60:61], s[60:61]
	v_and_b32_e32 v140, 0x7ff, v158
	v_add_u32_e32 v140, 16, v140
	s_or_b64 exec, exec, s[60:61]
	v_lshlrev_b64 v[162:163], 8, v[140:141]
	v_lshl_add_u64 v[162:163], v[142:143], 0, v[162:163]
	global_load_dwordx4 v[170:173], v[162:163], off offset:16
	global_load_dwordx4 v[174:177], v[162:163], off
	global_load_dwordx4 v[202:205], v[162:163], off offset:48
	global_load_dwordx4 v[206:209], v[162:163], off offset:32
	s_waitcnt vmcnt(0)
; __device__ __forceinline__ unsigned cvt_pk_bf16(float lo, float hi) { const cvt_f32x2 v = {lo, hi}; const cvt_bf16x2 b = __builtin_convertvector(v, cvt_bf16x2); return __builtin_bit_cast(unsigned, b); }
; #define EPI_ROWLOOP _Pragma("unroll") for (int ai = 0; ai < 2; ++ai) _Pragma("unroll") for (int m = 0; m < 4; ++m)
;     __device__ __forceinline__ void operator()(const f32x4 (&acc)[2][2][4][2], const Unit& u, int wr, int wc, int fr, int fq) const {
;     ...
;             bf16_t* QR = (bf16_t*)(ws + WS_R2); const float* ropecs = (const float*)(ws + WS_ROPE);
;             EPI_ROWLOOP { const int r = row0 + ai * HALF + m * 16; const f32x4 pq = part[r]; const float rs = __builtin_amdgcn_rsqf(((pq[0] + pq[1]) + (pq[2] + pq[3])) * (1.0f / 256.0f) + EP_EPS) * qscale;
;                 const float* t = ropecs + ((size_t)pos_of_row(r) * 32 + 8 * fq) * 2;
;                 bf16_t* rowp = QR + (size_t)r * 512 + (4 * (pn - 4) + wc) * 64 + 8 * fq;
; #pragma unroll
;                 for (int n = 0; n < 2; ++n) { f32x4 a = acc[ai][0][m][n], b = acc[ai][1][m][n]; rope4(a, b, t + 8 * n); a = a * rs; b = b * rs;
;                     *(u32x2*)(rowp + 4 * n) = (u32x2){cvt_pk_bf16(a[0], a[1]), cvt_pk_bf16(a[2], a[3])}; *(u32x2*)(rowp + 32 + 4 * n) = (u32x2){cvt_pk_bf16(b[0], b[1]), cvt_pk_bf16(b[2], b[3])};
;                     asm volatile("" ::: "memory"); } }
	v_add_f32_e32 v128, v128, v129
	v_add_f32_e32 v129, v130, v131
	v_add_f32_e32 v128, v128, v129
	v_fmamk_f32 v128, v128, 0x3b800000, v169
	v_rsq_f32_e32 v130, v128
	v_lshlrev_b64 v[128:129], 10, v[158:159]
	v_lshl_add_u64 v[178:179], v[160:161], 0, v[128:129]
	v_mul_f32_e32 v140, 0x3dd53b94, v130
	v_mov_b32_e32 v128, v171
	v_mov_b32_e32 v129, v173
	v_mov_b32_e32 v130, v175
	v_mov_b32_e32 v131, v177
	v_mov_b32_e32 v175, v176
	v_mov_b32_e32 v171, v172
	v_pk_mul_f32 v[158:159], v[6:7], v[128:129]
	v_pk_mul_f32 v[160:161], v[4:5], v[130:131]
	v_pk_mul_f32 v[172:173], v[6:7], v[170:171]
	v_pk_mul_f32 v[176:177], v[4:5], v[174:175]
	v_pk_fma_f32 v[160:161], v[12:13], v[174:175], v[160:161] neg_lo:[0,0,1] neg_hi:[0,0,1]
	v_pk_fma_f32 v[158:159], v[14:15], v[170:171], v[158:159] neg_lo:[0,0,1] neg_hi:[0,0,1]
	v_pk_fma_f32 v[130:131], v[12:13], v[130:131], v[176:177]
	v_pk_fma_f32 v[128:129], v[14:15], v[128:129], v[172:173]
	v_pk_mul_f32 v[158:159], v[140:141], v[158:159] op_sel_hi:[0,1]
	v_pk_mul_f32 v[160:161], v[140:141], v[160:161] op_sel_hi:[0,1]
	v_pk_mul_f32 v[128:129], v[140:141], v[128:129] op_sel_hi:[0,1]
	v_pk_mul_f32 v[130:131], v[140:141], v[130:131] op_sel_hi:[0,1]
	v_cvt_pk_bf16_f32 v160, v160, v161
	v_cvt_pk_bf16_f32 v161, v158, v159
	v_cvt_pk_bf16_f32 v130, v130, v131
	v_cvt_pk_bf16_f32 v131, v128, v129
	global_store_dwordx2 v[178:179], v[160:161], off
	global_store_dwordx2 v[178:179], v[130:131], off offset:64
	v_mov_b64_e32 v[128:129], v[202:203]
	v_mov_b64_e32 v[158:159], v[206:207]
	v_mov_b64_e32 v[130:131], v[204:205]
	v_mov_b64_e32 v[160:161], v[208:209]
	v_mov_b32_e32 v162, v129
	v_mov_b32_e32 v163, v131
	v_mov_b32_e32 v170, v159
	v_mov_b32_e32 v171, v161
	v_mov_b32_e32 v159, v160
	v_mov_b32_e32 v129, v130
	v_pk_mul_f32 v[130:131], v[2:3], v[162:163]
	v_pk_mul_f32 v[160:161], v[0:1], v[170:171]
	v_pk_mul_f32 v[172:173], v[2:3], v[128:129]
	v_pk_mul_f32 v[174:175], v[0:1], v[158:159]
	v_pk_fma_f32 v[158:159], v[8:9], v[158:159], v[160:161] neg_lo:[0,0,1] neg_hi:[0,0,1]
	v_pk_fma_f32 v[128:129], v[10:11], v[128:129], v[130:131] neg_lo:[0,0,1] neg_hi:[0,0,1]
	v_pk_fma_f32 v[130:131], v[8:9], v[170:171], v[174:175]
	v_pk_fma_f32 v[160:161], v[10:11], v[162:163], v[172:173]
	v_pk_mul_f32 v[128:129], v[140:141], v[128:129] op_sel_hi:[0,1]
	v_pk_mul_f32 v[158:159], v[140:141], v[158:159] op_sel_hi:[0,1]
	v_pk_mul_f32 v[160:161], v[140:141], v[160:161] op_sel_hi:[0,1]
	v_pk_mul_f32 v[130:131], v[140:141], v[130:131] op_sel_hi:[0,1]
	v_cvt_pk_bf16_f32 v158, v158, v159
	v_cvt_pk_bf16_f32 v159, v128, v129
	v_cvt_pk_bf16_f32 v128, v130, v131
	v_cvt_pk_bf16_f32 v129, v160, v161
	global_store_dwordx2 v[178:179], v[158:159], off offset:8
	global_store_dwordx2 v[178:179], v[128:129], off offset:72
	s_branch .LBB0_540
